# attention: V staged row-major (coalesced loads at K+256B), PV operands via ds_read_b64_tr_b16; unified mask+fast softmax; one-tile-deeper global prefetch
# speedup vs baseline: 1.0232x; 1.0232x over previous
.LBB0_39:
	s_lshl_b32 s0, s28, 7
	s_and_b32 s70, s0, 0x380000
	s_lshl_b32 s0, s28, 12
	s_and_b32 s1, s24, 7
	s_and_b32 s0, s0, 0x7000000
	s_lshl_b32 s1, s1, 9
	v_lshl_add_u64 v[210:211], v[196:197], 0, s[70:71]
	s_or_b32 s70, s1, s0
	s_lshl_b32 s0, s5, 8
	s_add_i32 s43, s0, s25
	s_lshl_b32 s1, s29, 9
	v_or_b32_e32 v208, s43, v189
	v_lshl_add_u64 v[212:213], s[70:71], 0, v[198:199]
	v_lshl_add_u64 v[214:215], s[70:71], 0, v[200:201]
	v_lshl_add_u64 v[216:217], s[70:71], 0, v[202:203]
	v_lshl_add_u64 v[218:219], s[70:71], 0, v[204:205]
	s_and_b32 s70, s1, 0x7000
	v_ashrrev_i32_e32 v209, 31, v208
	v_lshl_add_u64 v[206:207], v[208:209], 0, s[70:71]
	v_mov_b64_e32 v[0:1], s[14:15]
	s_and_b32 s42, s29, 7
	v_mad_u64_u32 v[0:1], s[38:39], v206, s10, v[0:1]
	v_mad_i32_i24 v1, v207, s10, v1
	s_mul_i32 s38, s42, 0x180
	s_mov_b32 s39, s71
	v_lshl_add_u64 v[0:1], v[0:1], 0, s[38:39]
	v_lshlrev_b64 v[20:21], 7, v[206:207]
	v_lshl_add_u64 v[4:5], v[0:1], 0, v[164:165]
	v_lshl_add_u64 v[34:35], v[192:193], 0, v[20:21]
	v_lshl_add_u64 v[20:21], v[194:195], 0, v[20:21]
	global_load_dwordx4 v[132:135], v[4:5], off
	global_load_dwordx4 v[128:131], v[4:5], off offset:32
	global_load_dwordx4 v[124:127], v[4:5], off offset:64
	global_load_dwordx4 v[116:119], v[4:5], off offset:96
	global_load_dwordx4 v[112:115], v[4:5], off offset:128
	global_load_dwordx4 v[104:107], v[4:5], off offset:160
	global_load_dwordx4 v[100:103], v[4:5], off offset:192
	global_load_dwordx4 v[96:99], v[4:5], off offset:224
	global_load_dwordx4 v[8:11], v[4:5], off offset:256
	global_load_dwordx4 v[0:3], v[4:5], off offset:288
	global_load_dwordx4 v[12:15], v[4:5], off offset:320
	s_nop 0
	global_load_dwordx4 v[4:7], v[4:5], off offset:352
	s_nop 0
	global_load_dwordx4 v[16:19], v[34:35], off offset:16
	global_load_dwordx4 v[22:25], v[34:35], off
	global_load_dwordx4 v[26:29], v[20:21], off offset:16
	global_load_dwordx4 v[30:33], v[20:21], off
	s_lshl_b32 s1, s70, 12
	s_add_u32 s1, s96, s1
	s_addc_u32 s5, s97, 0
	s_lshl_b32 s7, s42, 9
	s_add_u32 s38, s1, s7
	s_addc_u32 s39, s5, 0
	s_lshl_b32 s70, s70, 7
	s_or_b32 s44, s43, 31
	s_or_b32 s45, s0, 0xc0
	s_mov_b32 s46, 0
	v_mov_b32_e32 v209, 0
	v_mov_b32_e32 v247, 0xf149f2ca
	s_mov_b32 s13, 0
	s_waitcnt vmcnt(0)
	v_and_b32_e32 v37, 0xffff0000, v8
	v_lshlrev_b32_e32 v36, 16, v8
	s_waitcnt vmcnt(5)
	v_and_b32_e32 v39, 0xffff0000, v12
	v_lshlrev_b32_e32 v38, 16, v12
	v_lshlrev_b32_e32 v8, 16, v13
	s_waitcnt vmcnt(0)
	v_pk_mul_f32 v[40:41], v[30:31], v[36:37]
	v_pk_mul_f32 v[30:31], v[30:31], v[38:39]
	v_pk_fma_f32 v[40:41], v[22:23], v[38:39], v[40:41]
	v_pk_fma_f32 v[22:23], v[22:23], v[36:37], v[30:31] neg_lo:[0,0,1] neg_hi:[0,0,1]
	v_cvt_pk_bf16_f32 v108, v40, v41
	v_cvt_pk_bf16_f32 v120, v22, v23
	v_and_b32_e32 v23, 0xffff0000, v9
	v_lshlrev_b32_e32 v22, 16, v9
	v_and_b32_e32 v9, 0xffff0000, v13
	v_pk_mul_f32 v[12:13], v[32:33], v[22:23]
	s_nop 0
	v_pk_fma_f32 v[12:13], v[24:25], v[8:9], v[12:13]
	v_pk_mul_f32 v[8:9], v[32:33], v[8:9]
	v_cvt_pk_bf16_f32 v109, v12, v13
	v_pk_fma_f32 v[8:9], v[24:25], v[22:23], v[8:9] neg_lo:[0,0,1] neg_hi:[0,0,1]
	v_and_b32_e32 v13, 0xffff0000, v14
	v_cvt_pk_bf16_f32 v121, v8, v9
	v_and_b32_e32 v9, 0xffff0000, v10
	v_lshlrev_b32_e32 v8, 16, v10
	v_lshlrev_b32_e32 v12, 16, v14
	v_pk_mul_f32 v[22:23], v[26:27], v[8:9]
	v_lshlrev_b32_e32 v10, 16, v15
	v_pk_fma_f32 v[22:23], v[16:17], v[12:13], v[22:23]
	v_pk_mul_f32 v[12:13], v[26:27], v[12:13]
	v_cvt_pk_bf16_f32 v110, v22, v23
	v_pk_fma_f32 v[8:9], v[16:17], v[8:9], v[12:13] neg_lo:[0,0,1] neg_hi:[0,0,1]
	v_and_b32_e32 v25, 0xffff0000, v0
	v_cvt_pk_bf16_f32 v122, v8, v9
	v_and_b32_e32 v9, 0xffff0000, v11
	v_lshlrev_b32_e32 v8, 16, v11
	v_and_b32_e32 v11, 0xffff0000, v15
	v_pk_mul_f32 v[12:13], v[28:29], v[8:9]
	v_lshlrev_b32_e32 v24, 16, v0
	v_pk_fma_f32 v[12:13], v[18:19], v[10:11], v[12:13]
	v_pk_mul_f32 v[10:11], v[28:29], v[10:11]
	v_cvt_pk_bf16_f32 v111, v12, v13
	v_pk_fma_f32 v[8:9], v[18:19], v[8:9], v[10:11] neg_lo:[0,0,1] neg_hi:[0,0,1]
	v_and_b32_e32 v27, 0xffff0000, v4
	v_cvt_pk_bf16_f32 v123, v8, v9
	global_load_dwordx4 v[8:11], v[34:35], off offset:80
	global_load_dwordx4 v[16:19], v[34:35], off offset:64
	global_load_dwordx4 v[12:15], v[20:21], off offset:80
	s_nop 0
	global_load_dwordx4 v[20:23], v[20:21], off offset:64
	v_lshlrev_b32_e32 v26, 16, v4
	v_lshlrev_b32_e32 v0, 16, v5
	s_waitcnt vmcnt(0)
	v_pk_mul_f32 v[28:29], v[20:21], v[24:25]
	v_pk_mul_f32 v[20:21], v[20:21], v[26:27]
	v_pk_fma_f32 v[28:29], v[16:17], v[26:27], v[28:29]
	v_pk_fma_f32 v[16:17], v[16:17], v[24:25], v[20:21] neg_lo:[0,0,1] neg_hi:[0,0,1]
	v_cvt_pk_bf16_f32 v136, v28, v29
	v_cvt_pk_bf16_f32 v140, v16, v17
	v_and_b32_e32 v17, 0xffff0000, v1
	v_lshlrev_b32_e32 v16, 16, v1
	v_and_b32_e32 v1, 0xffff0000, v5
	v_pk_mul_f32 v[4:5], v[22:23], v[16:17]
	s_nop 0
	v_pk_fma_f32 v[4:5], v[18:19], v[0:1], v[4:5]
	v_pk_mul_f32 v[0:1], v[22:23], v[0:1]
	v_cvt_pk_bf16_f32 v137, v4, v5
	v_pk_fma_f32 v[0:1], v[18:19], v[16:17], v[0:1] neg_lo:[0,0,1] neg_hi:[0,0,1]
	v_and_b32_e32 v5, 0xffff0000, v6
	v_cvt_pk_bf16_f32 v141, v0, v1
	v_and_b32_e32 v1, 0xffff0000, v2
	v_lshlrev_b32_e32 v0, 16, v2
	v_lshlrev_b32_e32 v4, 16, v6
	v_pk_mul_f32 v[16:17], v[12:13], v[0:1]
	v_lshlrev_b32_e32 v2, 16, v7
	v_pk_fma_f32 v[16:17], v[8:9], v[4:5], v[16:17]
	v_pk_mul_f32 v[4:5], v[12:13], v[4:5]
	v_cvt_pk_bf16_f32 v138, v16, v17
	v_pk_fma_f32 v[0:1], v[8:9], v[0:1], v[4:5] neg_lo:[0,0,1] neg_hi:[0,0,1]
	v_lshl_add_u64 v[16:17], v[180:181], 1, s[38:39]
	v_cvt_pk_bf16_f32 v142, v0, v1
	v_and_b32_e32 v1, 0xffff0000, v3
	v_lshlrev_b32_e32 v0, 16, v3
	v_and_b32_e32 v3, 0xffff0000, v7
	v_pk_mul_f32 v[4:5], v[14:15], v[0:1]
	global_load_dwordx4 v[16:19], v[16:17], off offset:256
	v_pk_fma_f32 v[4:5], v[10:11], v[2:3], v[4:5]
	v_pk_mul_f32 v[2:3], v[14:15], v[2:3]
	v_cvt_pk_bf16_f32 v139, v4, v5
	v_pk_fma_f32 v[0:1], v[10:11], v[0:1], v[2:3] neg_lo:[0,0,1] neg_hi:[0,0,1]
	s_nop 0
	v_cvt_pk_bf16_f32 v143, v0, v1
	v_lshl_add_u64 v[0:1], v[180:181], 1, s[38:39]
	global_load_dwordx4 v[4:7], v[0:1], off
	v_lshl_add_u64 v[0:1], v[182:183], 1, s[38:39]
	global_load_dwordx4 v[8:11], v[0:1], off
	v_lshl_add_u64 v[0:1], v[190:191], 0, s[70:71]
	global_load_dwordx4 v[12:15], v[0:1], off
	v_lshl_add_u64 v[0:1], v[182:183], 1, s[38:39]
	global_load_dwordx4 v[0:3], v[0:1], off offset:256
	s_waitcnt vmcnt(0)
	ds_write_b128 v244, v[4:7]
	s_waitcnt vmcnt(2)
	ds_write_b128 v244, v[8:11] offset:12800
	s_waitcnt vmcnt(1)
	ds_write_b128 v245, v[12:15] offset:256
	v_mov_b32_e32 v14, v165
	v_mov_b32_e32 v15, v165
	s_waitcnt vmcnt(0)
	s_movk_i32 s0, 320
	s_movk_i32 s1, 1280
	v_lshrrev_b32_e32 v216, 4, v220
	v_mul_u32_u24_e32 v216, s0, v216
	v_and_b32_e32 v248, 15, v220
	v_lshl_add_u32 v216, v248, 4, v216
	v_and_b32_e32 v217, 3, v220
	v_lshlrev_b32_e32 v217, 3, v217
	v_bfe_u32 v248, v220, 2, 2
	v_mad_u32_u24 v217, v248, s0, v217
	v_bfe_u32 v248, v220, 4, 1
	v_lshl_add_u32 v217, v248, 5, v217
	v_bfe_u32 v248, v220, 5, 1
	v_mad_u32_u24 v217, v248, s1, v217
	ds_write_b128 v216, v[16:19] offset:51200
	ds_write_b128 v216, v[0:3] offset:61440
	v_mov_b32_e32 v0, v165
	v_mov_b32_e32 v1, v165
	v_mov_b32_e32 v2, v165
	v_mov_b32_e32 v3, v165
	v_mov_b32_e32 v4, v165
	v_mov_b32_e32 v5, v165
	v_mov_b32_e32 v6, v165
	v_mov_b32_e32 v7, v165
	v_mov_b32_e32 v8, v165
	v_mov_b32_e32 v9, v165
	v_mov_b32_e32 v10, v165
	v_mov_b32_e32 v11, v165
	v_mov_b32_e32 v12, v165
	v_mov_b32_e32 v13, v165
	v_mov_b64_e32 v[30:31], v[14:15]
	v_mov_b64_e32 v[46:47], v[14:15]
	v_mov_b64_e32 v[62:63], v[14:15]
	v_mov_b64_e32 v[28:29], v[12:13]
	v_mov_b64_e32 v[26:27], v[10:11]
	v_mov_b64_e32 v[24:25], v[8:9]
	v_mov_b64_e32 v[22:23], v[6:7]
	v_mov_b64_e32 v[20:21], v[4:5]
	v_mov_b64_e32 v[18:19], v[2:3]
	v_mov_b64_e32 v[16:17], v[0:1]
	v_mov_b64_e32 v[44:45], v[12:13]
	v_mov_b64_e32 v[42:43], v[10:11]
	v_mov_b64_e32 v[40:41], v[8:9]
	v_mov_b64_e32 v[38:39], v[6:7]
	v_mov_b64_e32 v[36:37], v[4:5]
	v_mov_b64_e32 v[34:35], v[2:3]
	v_mov_b64_e32 v[32:33], v[0:1]
	v_mov_b64_e32 v[60:61], v[12:13]
	v_mov_b64_e32 v[58:59], v[10:11]
	v_mov_b64_e32 v[56:57], v[8:9]
	v_mov_b64_e32 v[54:55], v[6:7]
	v_mov_b64_e32 v[52:53], v[4:5]
	v_mov_b64_e32 v[50:51], v[2:3]
	v_mov_b64_e32 v[48:49], v[0:1]
	s_waitcnt lgkmcnt(0)
	s_barrier
	v_lshl_add_u64 v[248:249], s[20:21], 0, v[212:213]
	global_load_dwordx4 v[152:155], v[248:249], off
	v_lshl_add_u64 v[170:171], s[20:21], 0, v[214:215]
	global_load_dwordx4 v[156:159], v[170:171], off
	v_lshl_add_u64 v[218:219], s[20:21], 0, v[210:211]
	global_load_dwordx4 v[160:163], v[218:219], off
	global_load_dwordx4 v[144:147], v[248:249], off offset:256
	global_load_dwordx4 v[148:151], v[170:171], off offset:256
	s_mov_b64 s[38:39], 0x2000
	v_lshl_add_u64 v[210:211], v[210:211], 0, s[38:39]
	v_lshl_add_u64 v[212:213], v[212:213], 0, s[72:73]
	v_lshl_add_u64 v[214:215], v[214:215], 0, s[72:73]

.Lat_stage:
	s_cmp_eq_u32 s46, s45
	s_cbranch_scc1 .Lat_nostage
	s_xor_b32 s7, s5, 1
	s_mul_i32 s9, s7, 0x6400
	v_add3_u32 v172, s9, v236, v237
	s_waitcnt vmcnt(4)
	ds_write_b128 v172, v[152:155]
	s_waitcnt vmcnt(3)
	ds_write_b128 v172, v[156:159] offset:12800
	v_add3_u32 v173, s9, v238, v239
	s_waitcnt vmcnt(2)
	ds_write_b128 v173, v[160:163] offset:256
	s_mul_i32 s7, s7, 20480
	v_add_u32_e32 v173, s7, v216
	s_waitcnt vmcnt(1)
	ds_write_b128 v173, v[144:147] offset:51200
	s_waitcnt vmcnt(0)
	ds_write_b128 v173, v[148:151] offset:61440
	s_add_i32 s7, s46, 64
	s_cmp_eq_u32 s7, s45
	s_cbranch_scc1 .Lat_nostage
	v_lshl_add_u64 v[248:249], s[20:21], 0, v[212:213]
	global_load_dwordx4 v[152:155], v[248:249], off
	v_lshl_add_u64 v[170:171], s[20:21], 0, v[214:215]
	global_load_dwordx4 v[156:159], v[170:171], off
	v_lshl_add_u64 v[218:219], s[20:21], 0, v[210:211]
	global_load_dwordx4 v[160:163], v[218:219], off
	global_load_dwordx4 v[144:147], v[248:249], off offset:256
	global_load_dwordx4 v[148:151], v[170:171], off offset:256
	s_mov_b64 s[38:39], 0x2000
	v_lshl_add_u64 v[210:211], v[210:211], 0, s[38:39]
	v_lshl_add_u64 v[212:213], v[212:213], 0, s[72:73]
	v_lshl_add_u64 v[214:215], v[214:215], 0, s[72:73]
.Lat_nostage:
	s_andn2_b64 vcc, exec, s[0:1]
	s_cbranch_vccnz .Lat_novis
	s_mul_i32 s5, s5, 20480
	s_add_i32 s5, s5, 51200
	v_add_u32_e32 v250, s5, v217
	ds_read_b64_tr_b16 v[166:167], v250 offset:0
	ds_read_b64_tr_b16 v[168:169], v250 offset:2560
	ds_read_b64_tr_b16 v[172:173], v250 offset:5120
	ds_read_b64_tr_b16 v[174:175], v250 offset:7680
	ds_read_b64_tr_b16 v[176:177], v250 offset:10240
	ds_read_b64_tr_b16 v[178:179], v250 offset:12800
	ds_read_b64_tr_b16 v[222:223], v250 offset:15360
	ds_read_b64_tr_b16 v[224:225], v250 offset:17920
	ds_read_b64_tr_b16 v[228:229], v250 offset:64
	ds_read_b64_tr_b16 v[230:231], v250 offset:2624
	ds_read_b64_tr_b16 v[232:233], v250 offset:5184
	ds_read_b64_tr_b16 v[234:235], v250 offset:7744
	s_add_i32 s0, s46, 63
	s_cmp_gt_i32 s0, s43
	s_cbranch_scc0 .Lat_fast
	v_sub_u32_e32 v227, v208, v188
	v_subrev_u32_e32 v227, s46, v227
	v_cmp_gt_i32_e32 vcc, 0, v227
	v_cmp_gt_i32_e64 s[0:1], 1, v227
	v_cmp_gt_i32_e64 s[38:39], 2, v227
	v_cndmask_b32_e32 v64, v64, v226, vcc
	v_cmp_gt_i32_e32 vcc, 3, v227
	v_cndmask_b32_e64 v65, v65, v226, s[0:1]
	v_cmp_gt_i32_e64 s[0:1], 8, v227
	v_cndmask_b32_e64 v66, v66, v226, s[38:39]
	v_cmp_gt_i32_e64 s[38:39], 9, v227
	v_cndmask_b32_e32 v67, v67, v226, vcc
	v_cmp_gt_i32_e32 vcc, 10, v227
	v_cndmask_b32_e64 v68, v68, v226, s[0:1]
	v_cmp_gt_i32_e64 s[0:1], 11, v227
	v_cndmask_b32_e64 v69, v69, v226, s[38:39]
	v_cmp_gt_i32_e64 s[38:39], 16, v227
	v_cndmask_b32_e32 v70, v70, v226, vcc
	v_cmp_gt_i32_e32 vcc, 17, v227
	v_cndmask_b32_e64 v71, v71, v226, s[0:1]
	v_cmp_gt_i32_e64 s[0:1], 18, v227
	v_cndmask_b32_e64 v72, v72, v226, s[38:39]
	v_cmp_gt_i32_e64 s[38:39], 19, v227
	v_cndmask_b32_e32 v73, v73, v226, vcc
	v_cmp_gt_i32_e32 vcc, 24, v227
	v_cndmask_b32_e64 v74, v74, v226, s[0:1]
	v_cmp_gt_i32_e64 s[0:1], 25, v227
	v_cndmask_b32_e64 v75, v75, v226, s[38:39]
	v_cmp_gt_i32_e64 s[38:39], 26, v227
	v_cndmask_b32_e32 v76, v76, v226, vcc
	v_cmp_gt_i32_e32 vcc, 27, v227
	v_cndmask_b32_e64 v77, v77, v226, s[0:1]
	v_cmp_gt_i32_e64 s[0:1], 32, v227
	v_cndmask_b32_e64 v78, v78, v226, s[38:39]
	v_cmp_gt_i32_e64 s[38:39], 33, v227
	v_cndmask_b32_e32 v79, v79, v226, vcc
	v_cmp_gt_i32_e32 vcc, 34, v227
	v_cndmask_b32_e64 v80, v80, v226, s[0:1]
	v_cmp_gt_i32_e64 s[0:1], 35, v227
	v_cndmask_b32_e64 v81, v81, v226, s[38:39]
	v_cmp_gt_i32_e64 s[38:39], 40, v227
	v_cndmask_b32_e32 v82, v82, v226, vcc
	v_cmp_gt_i32_e32 vcc, 41, v227
	v_cndmask_b32_e64 v83, v83, v226, s[0:1]
	v_cmp_gt_i32_e64 s[0:1], 42, v227
	v_cndmask_b32_e64 v84, v84, v226, s[38:39]
	v_cmp_gt_i32_e64 s[38:39], 43, v227
	v_cndmask_b32_e32 v85, v85, v226, vcc
	v_cmp_gt_i32_e32 vcc, 48, v227
	v_cndmask_b32_e64 v86, v86, v226, s[0:1]
	v_cmp_gt_i32_e64 s[0:1], 49, v227
	v_cndmask_b32_e64 v87, v87, v226, s[38:39]
	v_cmp_gt_i32_e64 s[38:39], 50, v227
	v_cndmask_b32_e32 v88, v88, v226, vcc
	v_cmp_gt_i32_e32 vcc, 51, v227
	v_cndmask_b32_e64 v89, v89, v226, s[0:1]
	v_cmp_gt_i32_e64 s[0:1], 56, v227
	v_cndmask_b32_e64 v90, v90, v226, s[38:39]
	v_cmp_gt_i32_e64 s[38:39], 57, v227
	v_cndmask_b32_e32 v91, v91, v226, vcc
	v_cmp_gt_i32_e32 vcc, 58, v227
	v_cndmask_b32_e64 v92, v92, v226, s[0:1]
	v_cmp_gt_i32_e64 s[0:1], 59, v227
	v_cndmask_b32_e64 v93, v93, v226, s[38:39]
	s_nop 1
	v_cndmask_b32_e32 v94, v94, v226, vcc
	v_cndmask_b32_e64 v95, v95, v226, s[0:1]
.Lat_fast:
	v_max3_f32 v227, v64, v65, v66
	v_max3_f32 v248, v73, v74, v75
	v_max3_f32 v249, v80, v81, v82
	v_max3_f32 v170, v89, v90, v91
	v_max3_f32 v227, v227, v67, v68
	v_max3_f32 v248, v248, v76, v77
	v_max3_f32 v249, v249, v83, v84
	v_max3_f32 v170, v170, v92, v93
	v_max3_f32 v227, v227, v69, v70
	v_max3_f32 v248, v248, v78, v79
	v_max3_f32 v249, v249, v85, v86
	v_max3_f32 v170, v170, v94, v95
	v_max3_f32 v227, v227, v71, v72
	v_max3_f32 v249, v249, v87, v88
	v_max3_f32 v227, v227, v248, v226
	v_max3_f32 v227, v227, v249, v170
	v_mov_b32_e32 v248, v227
	s_nop 1
	v_permlane32_swap_b32_e32 v227, v248
	v_max_f32_e32 v227, v227, v248
	v_mul_f32_e32 v227, 0x3dd53b94, v227
	v_max_f32_e32 v221, v247, v227
	v_sub_f32_e32 v170, v247, v221
	v_exp_f32_e32 v170, v170
	v_cmp_gt_f32_e32 vcc, v221, v247
	s_cbranch_vccz .Lat_fast_nr
	v_pk_mul_f32 v[62:63], v[62:63], v[170:171] op_sel_hi:[1,0]
	v_pk_mul_f32 v[60:61], v[60:61], v[170:171] op_sel_hi:[1,0]
	v_pk_mul_f32 v[58:59], v[58:59], v[170:171] op_sel_hi:[1,0]
	v_pk_mul_f32 v[56:57], v[56:57], v[170:171] op_sel_hi:[1,0]
	v_pk_mul_f32 v[54:55], v[54:55], v[170:171] op_sel_hi:[1,0]
	v_pk_mul_f32 v[52:53], v[52:53], v[170:171] op_sel_hi:[1,0]
	v_pk_mul_f32 v[50:51], v[50:51], v[170:171] op_sel_hi:[1,0]
	v_pk_mul_f32 v[48:49], v[48:49], v[170:171] op_sel_hi:[1,0]
	v_pk_mul_f32 v[46:47], v[46:47], v[170:171] op_sel_hi:[1,0]
	v_pk_mul_f32 v[44:45], v[44:45], v[170:171] op_sel_hi:[1,0]
	v_pk_mul_f32 v[42:43], v[42:43], v[170:171] op_sel_hi:[1,0]
	v_pk_mul_f32 v[40:41], v[40:41], v[170:171] op_sel_hi:[1,0]
	v_pk_mul_f32 v[38:39], v[38:39], v[170:171] op_sel_hi:[1,0]
	v_pk_mul_f32 v[36:37], v[36:37], v[170:171] op_sel_hi:[1,0]
	v_pk_mul_f32 v[34:35], v[34:35], v[170:171] op_sel_hi:[1,0]
	v_pk_mul_f32 v[32:33], v[32:33], v[170:171] op_sel_hi:[1,0]
	v_pk_mul_f32 v[30:31], v[30:31], v[170:171] op_sel_hi:[1,0]
	v_pk_mul_f32 v[28:29], v[28:29], v[170:171] op_sel_hi:[1,0]
	v_pk_mul_f32 v[26:27], v[26:27], v[170:171] op_sel_hi:[1,0]
	v_pk_mul_f32 v[24:25], v[24:25], v[170:171] op_sel_hi:[1,0]
	v_pk_mul_f32 v[22:23], v[22:23], v[170:171] op_sel_hi:[1,0]
	v_pk_mul_f32 v[20:21], v[20:21], v[170:171] op_sel_hi:[1,0]
	v_pk_mul_f32 v[18:19], v[18:19], v[170:171] op_sel_hi:[1,0]
	v_pk_mul_f32 v[16:17], v[16:17], v[170:171] op_sel_hi:[1,0]
	v_pk_mul_f32 v[14:15], v[14:15], v[170:171] op_sel_hi:[1,0]
	v_pk_mul_f32 v[12:13], v[12:13], v[170:171] op_sel_hi:[1,0]
	v_pk_mul_f32 v[10:11], v[10:11], v[170:171] op_sel_hi:[1,0]
	v_pk_mul_f32 v[8:9], v[8:9], v[170:171] op_sel_hi:[1,0]
	v_pk_mul_f32 v[6:7], v[6:7], v[170:171] op_sel_hi:[1,0]
	v_pk_mul_f32 v[4:5], v[4:5], v[170:171] op_sel_hi:[1,0]
	v_pk_mul_f32 v[2:3], v[2:3], v[170:171] op_sel_hi:[1,0]
	v_pk_mul_f32 v[0:1], v[0:1], v[170:171] op_sel_hi:[1,0]
.Lat_fast_nr:
	v_fma_f32 v64, v64, s6, -v221
	v_fma_f32 v80, v80, s6, -v221
	v_exp_f32_e32 v64, v64
	v_exp_f32_e32 v80, v80
	v_fma_f32 v65, v65, s6, -v221
	v_fma_f32 v81, v81, s6, -v221
	v_add_f32_e32 v248, v64, v80
	v_exp_f32_e32 v65, v65
	v_exp_f32_e32 v81, v81
	v_mov_b32_e32 v249, v248
	v_fma_f32 v66, v66, s6, -v221
	v_fma_f32 v82, v82, s6, -v221
	v_add_f32_e32 v248, v65, v81
	v_exp_f32_e32 v66, v66
	v_exp_f32_e32 v82, v82
	v_add_f32_e32 v249, v248, v249
	v_fma_f32 v67, v67, s6, -v221
	v_fma_f32 v83, v83, s6, -v221
	v_add_f32_e32 v248, v66, v82
	v_exp_f32_e32 v67, v67
	v_exp_f32_e32 v83, v83
	v_add_f32_e32 v249, v248, v249
	v_fma_f32 v68, v68, s6, -v221
	v_fma_f32 v84, v84, s6, -v221
	v_add_f32_e32 v248, v67, v83
	v_exp_f32_e32 v68, v68
	v_exp_f32_e32 v84, v84
	v_add_f32_e32 v249, v248, v249
	v_fma_f32 v69, v69, s6, -v221
	v_fma_f32 v85, v85, s6, -v221
	v_add_f32_e32 v248, v68, v84
	v_exp_f32_e32 v69, v69
	v_exp_f32_e32 v85, v85
	v_add_f32_e32 v249, v248, v249
	v_fma_f32 v70, v70, s6, -v221
	v_fma_f32 v86, v86, s6, -v221
	v_add_f32_e32 v248, v69, v85
	v_exp_f32_e32 v70, v70
	v_exp_f32_e32 v86, v86
	v_add_f32_e32 v249, v248, v249
	v_fma_f32 v71, v71, s6, -v221
	v_fma_f32 v87, v87, s6, -v221
	v_add_f32_e32 v248, v70, v86
	v_exp_f32_e32 v71, v71
	v_exp_f32_e32 v87, v87
	v_add_f32_e32 v249, v248, v249
	v_fma_f32 v72, v72, s6, -v221
	v_fma_f32 v88, v88, s6, -v221
	v_add_f32_e32 v248, v71, v87
	v_exp_f32_e32 v72, v72
	v_exp_f32_e32 v88, v88
	v_add_f32_e32 v249, v248, v249
	v_fma_f32 v73, v73, s6, -v221
	v_fma_f32 v89, v89, s6, -v221
	v_add_f32_e32 v248, v72, v88
	v_exp_f32_e32 v73, v73
	v_exp_f32_e32 v89, v89
	v_add_f32_e32 v249, v248, v249
	v_fma_f32 v74, v74, s6, -v221
	v_fma_f32 v90, v90, s6, -v221
	v_add_f32_e32 v248, v73, v89
	v_exp_f32_e32 v74, v74
	v_exp_f32_e32 v90, v90
	v_add_f32_e32 v249, v248, v249
	v_fma_f32 v75, v75, s6, -v221
	v_fma_f32 v91, v91, s6, -v221
	v_add_f32_e32 v248, v74, v90
	v_exp_f32_e32 v75, v75
	v_exp_f32_e32 v91, v91
	v_add_f32_e32 v249, v248, v249
	v_fma_f32 v76, v76, s6, -v221
	v_fma_f32 v92, v92, s6, -v221
	v_add_f32_e32 v248, v75, v91
	v_exp_f32_e32 v76, v76
	v_exp_f32_e32 v92, v92
	v_add_f32_e32 v249, v248, v249
	v_fma_f32 v77, v77, s6, -v221
	v_fma_f32 v93, v93, s6, -v221
	v_add_f32_e32 v248, v76, v92
	v_exp_f32_e32 v77, v77
	v_exp_f32_e32 v93, v93
	v_add_f32_e32 v249, v248, v249
	v_fma_f32 v78, v78, s6, -v221
	v_fma_f32 v94, v94, s6, -v221
	v_add_f32_e32 v248, v77, v93
	v_exp_f32_e32 v78, v78
	v_exp_f32_e32 v94, v94
	v_add_f32_e32 v249, v248, v249
	v_fma_f32 v79, v79, s6, -v221
	v_fma_f32 v95, v95, s6, -v221
	v_add_f32_e32 v248, v78, v94
	v_exp_f32_e32 v79, v79
	v_exp_f32_e32 v95, v95
	v_add_f32_e32 v249, v248, v249
	s_nop 0
	v_add_f32_e32 v248, v79, v95
	v_add_f32_e32 v249, v248, v249
	v_fmac_f32_e32 v249, v209, v170
	v_cvt_pk_bf16_f32 v72, v72, v73
	v_cvt_pk_bf16_f32 v73, v74, v75
	v_cvt_pk_bf16_f32 v74, v76, v77
	v_cvt_pk_bf16_f32 v75, v78, v79
	v_cvt_pk_bf16_f32 v76, v64, v65
	v_cvt_pk_bf16_f32 v77, v66, v67
	v_cvt_pk_bf16_f32 v78, v68, v69
	v_cvt_pk_bf16_f32 v79, v70, v71
	v_cvt_pk_bf16_f32 v68, v80, v81
	v_cvt_pk_bf16_f32 v69, v82, v83
	v_cvt_pk_bf16_f32 v70, v84, v85
	v_cvt_pk_bf16_f32 v71, v86, v87
	v_cvt_pk_bf16_f32 v64, v88, v89
	v_cvt_pk_bf16_f32 v65, v90, v91
	v_cvt_pk_bf16_f32 v66, v92, v93
	v_cvt_pk_bf16_f32 v67, v94, v95
	v_mov_b32_e32 v209, v249
	s_nop 1
	s_waitcnt lgkmcnt(10)
	v_mfma_f32_32x32x16_bf16 v[48:63], v[166:169], v[76:79], v[48:63]
	ds_read_b64_tr_b16 v[166:167], v250 offset:10304
	ds_read_b64_tr_b16 v[168:169], v250 offset:12864
	s_waitcnt lgkmcnt(10)
	v_mfma_f32_32x32x16_bf16 v[48:63], v[172:175], v[72:75], v[48:63]
	ds_read_b64_tr_b16 v[172:173], v250 offset:15424
	ds_read_b64_tr_b16 v[174:175], v250 offset:17984
	s_waitcnt lgkmcnt(10)
	v_mfma_f32_32x32x16_bf16 v[48:63], v[176:179], v[68:71], v[48:63]
	ds_read_b64_tr_b16 v[176:177], v250 offset:128
	ds_read_b64_tr_b16 v[178:179], v250 offset:2688
	s_waitcnt lgkmcnt(10)
	v_mfma_f32_32x32x16_bf16 v[48:63], v[222:225], v[64:67], v[48:63]
	ds_read_b64_tr_b16 v[222:223], v250 offset:5248
	ds_read_b64_tr_b16 v[224:225], v250 offset:7808
	s_waitcnt lgkmcnt(10)
	v_mfma_f32_32x32x16_bf16 v[32:47], v[228:231], v[76:79], v[32:47]
	ds_read_b64_tr_b16 v[228:229], v250 offset:10368
	ds_read_b64_tr_b16 v[230:231], v250 offset:12928
	s_waitcnt lgkmcnt(10)
	v_mfma_f32_32x32x16_bf16 v[32:47], v[232:235], v[72:75], v[32:47]
	ds_read_b64_tr_b16 v[232:233], v250 offset:15488
	ds_read_b64_tr_b16 v[234:235], v250 offset:18048
	s_waitcnt lgkmcnt(10)
	v_mfma_f32_32x32x16_bf16 v[32:47], v[166:169], v[68:71], v[32:47]
	ds_read_b64_tr_b16 v[166:167], v250 offset:192
	ds_read_b64_tr_b16 v[168:169], v250 offset:2752
	s_waitcnt lgkmcnt(10)
	v_mfma_f32_32x32x16_bf16 v[32:47], v[172:175], v[64:67], v[32:47]
	ds_read_b64_tr_b16 v[172:173], v250 offset:5312
	ds_read_b64_tr_b16 v[174:175], v250 offset:7872
	s_waitcnt lgkmcnt(10)
	v_mfma_f32_32x32x16_bf16 v[16:31], v[176:179], v[76:79], v[16:31]
	ds_read_b64_tr_b16 v[176:177], v250 offset:10432
	ds_read_b64_tr_b16 v[178:179], v250 offset:12992
	s_waitcnt lgkmcnt(10)
	v_mfma_f32_32x32x16_bf16 v[16:31], v[222:225], v[72:75], v[16:31]
	ds_read_b64_tr_b16 v[222:223], v250 offset:15552
	ds_read_b64_tr_b16 v[224:225], v250 offset:18112
	s_waitcnt lgkmcnt(10)
	v_mfma_f32_32x32x16_bf16 v[16:31], v[228:231], v[68:71], v[16:31]
	s_waitcnt lgkmcnt(8)
	v_mfma_f32_32x32x16_bf16 v[16:31], v[232:235], v[64:67], v[16:31]
	s_waitcnt lgkmcnt(6)
	v_mfma_f32_32x32x16_bf16 v[0:15], v[166:169], v[76:79], v[0:15]
	s_waitcnt lgkmcnt(4)
	v_mfma_f32_32x32x16_bf16 v[0:15], v[172:175], v[72:75], v[0:15]
	s_waitcnt lgkmcnt(2)
	v_mfma_f32_32x32x16_bf16 v[0:15], v[176:179], v[68:71], v[0:15]
	s_waitcnt lgkmcnt(0)
	v_mfma_f32_32x32x16_bf16 v[0:15], v[222:225], v[64:67], v[0:15]
	v_mov_b32_e32 v247, v221
.Lat_novis:
	s_cmp_eq_u32 s46, s45
	s_cbranch_scc1 .LBB0_32
	s_add_i32 s46, s46, 64
	s_add_i32 s13, s13, 1
	s_waitcnt lgkmcnt(0)
	s_barrier
	s_branch .LBB0_40
.LBB0_52:
	v_mov_b64_e32 v[166:167], 0x400
	v_mov_b64_e32 v[168:169], 0xff
	v_mov_b64_e32 v[176:177], 0xaff
	v_mov_b64_e32 v[178:179], 0xb00
	v_mov_b32_e32 v222, 0x3e91f4c4
	v_mov_b32_e32 v223, 0x3c0881c4
	v_mov_b32_e32 v224, 0xbab64f3b
	v_mov_b32_e32 v225, 1
	v_mov_b32_e32 v228, 0x1100
	v_mov_b32_e32 v229, 0x41b17218
	v_mov_b32_e32 v230, 0x461c4000
	v_mov_b32_e32 v231, 0x37000000
	v_mov_b32_e32 v232, 0x7f800000
	v_not_b32_e32 v233, 63
	v_not_b32_e32 v234, 31
	v_mov_b32_e32 v235, 0x7fc00000
	v_mov_b32_e32 v221, 0x358637bd
	v_mbcnt_lo_u32_b32 v227, -1, 0
	v_mbcnt_hi_u32_b32 v227, -1, v227
	v_mov_b64_e32 v[170:171], 0x100
	v_mov_b64_e32 v[248:249], 0x3ff
	s_mov_b64 s[0:1], 0
